# v41 with the transcendental-hazard s_nop slots of the softmax groups filled by an independent instruction (next exp, MFMA or address add) in both attention loops
# speedup vs baseline: 1.0041x; 1.0026x over previous
.LBB0_441:
	s_and_b32 s48, s33, 2
	s_add_i32 s4, s33, -1
	s_and_b32 s49, s4, 3
	s_mul_i32 s4, s48, 0x4800
	v_add_u32_e32 v168, s4, v184
	s_cmp_eq_u32 s33, 0
	ds_read_b128 v[164:167], v168 offset:96
	s_cselect_b64 s[6:7], -1, 0
	s_mulk_i32 s49, 0x4800
	s_and_b64 s[4:5], s[6:7], exec
	s_cselect_b32 s4, 0, s49
	v_exp_f32_e32 v64, v64
	v_exp_f32_e32 v65, v65
	v_add_u32_e32 v84, s4, v184
	v_add_f32_e32 v113, v65, v64
	v_cvt_pk_bf16_f32 v112, v64, v65
	ds_read_b128 v[186:189], v84 offset:9280
	ds_read_b128 v[190:193], v84 offset:9312
	ds_read_b128 v[194:197], v84 offset:13888
	ds_read_b128 v[198:201], v84 offset:13920
	v_mfma_f32_32x32x16_bf16 v[80:95], v[80:83], v[148:151], 0
	v_exp_f32_e32 v64, v66
	v_exp_f32_e32 v65, v67
	v_add_f32_e32 v66, v64, v113
	v_add_f32_e32 v66, v65, v66
	v_cvt_pk_bf16_f32 v113, v64, v65
	v_mfma_f32_32x32x16_bf16 v[80:95], v[108:111], v[152:155], v[80:95]
	v_exp_f32_e32 v64, v68
	v_exp_f32_e32 v65, v69
	v_add_f32_e32 v66, v64, v66
	v_cvt_pk_bf16_f32 v114, v64, v65
	v_add_f32_e32 v64, v65, v66
	v_mfma_f32_32x32x16_bf16 v[80:95], v[104:107], v[156:159], v[80:95]
	v_exp_f32_e32 v65, v70
	v_exp_f32_e32 v66, v71
	v_add_f32_e32 v64, v65, v64
	v_cvt_pk_bf16_f32 v115, v65, v66
	v_add_f32_e32 v64, v66, v64
	s_waitcnt lgkmcnt(4)
	v_mfma_f32_32x32x16_bf16 v[80:95], v[164:167], v[160:163], v[80:95]
	v_exp_f32_e32 v65, v72
	v_exp_f32_e32 v66, v73
	v_add_f32_e32 v64, v65, v64
	v_cvt_pk_bf16_f32 v104, v65, v66
	v_add_f32_e32 v64, v66, v64
	s_waitcnt lgkmcnt(0)
	v_mfma_f32_32x32x16_bf16 v[16:31], v[186:189], v[96:99], v[16:31]
	v_exp_f32_e32 v65, v74
	v_exp_f32_e32 v66, v75
	v_add_f32_e32 v64, v65, v64
	v_cvt_pk_bf16_f32 v105, v65, v66
	v_add_f32_e32 v64, v66, v64
	v_mfma_f32_32x32x16_bf16 v[16:31], v[190:193], v[100:103], v[16:31]
	v_exp_f32_e32 v65, v76
	v_exp_f32_e32 v66, v77
	v_add_f32_e32 v64, v65, v64
	v_cvt_pk_bf16_f32 v106, v65, v66
	v_add_f32_e32 v64, v66, v64
	v_mfma_f32_32x32x16_bf16 v[0:15], v[194:197], v[96:99], v[0:15]
	v_exp_f32_e32 v65, v78
	v_exp_f32_e32 v66, v79
	v_add_f32_e32 v64, v65, v64
	v_cvt_pk_bf16_f32 v107, v65, v66
	v_add_f32_e32 v185, v66, v64
	v_exp_f32_e32 v68, v80
	v_exp_f32_e32 v69, v81
	v_mfma_f32_32x32x16_bf16 v[0:15], v[198:201], v[100:103], v[0:15]
	v_add_f32_e32 v80, v69, v68
	v_cvt_pk_bf16_f32 v96, v68, v69
	ds_read_b128 v[64:67], v168 offset:4608
	ds_read_b128 v[164:167], v168 offset:4640
	ds_read_b128 v[108:111], v168 offset:4672
	v_cmp_nge_f32_e64 s[4:5], s62, v185
	v_cmp_gt_f32_e32 vcc, s75, v185
	s_and_b64 vcc, s[6:7], vcc
	s_or_b64 s[4:5], s[4:5], vcc
	ds_read_b128 v[186:189], v168 offset:4704
	s_waitcnt lgkmcnt(1)
	v_mfma_f32_32x32x16_bf16 v[64:79], v[64:67], v[116:119], 0
	ds_read_b128 v[190:193], v168 offset:9216
	ds_read_b128 v[194:197], v168 offset:9248
	ds_read_b128 v[198:201], v168 offset:13824
	ds_read_b128 v[230:233], v168 offset:13856
	v_exp_f32_e32 v81, v82
	v_exp_f32_e32 v82, v83
	v_add_f32_e32 v80, v81, v80
	v_add_f32_e32 v80, v82, v80
	v_cvt_pk_bf16_f32 v97, v81, v82
	v_mfma_f32_32x32x16_bf16 v[64:79], v[164:167], v[120:123], v[64:79]
	v_exp_f32_e32 v81, v84
	v_exp_f32_e32 v82, v85
	v_add_f32_e32 v80, v81, v80
	v_cvt_pk_bf16_f32 v98, v81, v82
	v_add_f32_e32 v80, v82, v80
	v_mfma_f32_32x32x16_bf16 v[64:79], v[108:111], v[124:127], v[64:79]
	v_exp_f32_e32 v81, v86
	v_exp_f32_e32 v82, v87
	v_add_f32_e32 v80, v81, v80
	v_cvt_pk_bf16_f32 v99, v81, v82
	v_add_f32_e32 v80, v82, v80
	s_waitcnt lgkmcnt(4)
	v_mfma_f32_32x32x16_bf16 v[64:79], v[186:189], v[128:131], v[64:79]
	v_exp_f32_e32 v81, v88
	v_exp_f32_e32 v82, v89
	v_add_f32_e32 v80, v81, v80
	v_cvt_pk_bf16_f32 v100, v81, v82
	v_add_f32_e32 v80, v82, v80
	s_waitcnt lgkmcnt(0)
	v_mfma_f32_32x32x16_bf16 v[48:63], v[190:193], v[112:115], v[48:63]
	v_exp_f32_e32 v81, v90
	v_exp_f32_e32 v82, v91
	v_add_f32_e32 v80, v81, v80
	v_cvt_pk_bf16_f32 v101, v81, v82
	v_add_f32_e32 v80, v82, v80
	v_mfma_f32_32x32x16_bf16 v[48:63], v[194:197], v[104:107], v[48:63]
	v_exp_f32_e32 v81, v92
	v_exp_f32_e32 v82, v93
	v_add_f32_e32 v80, v81, v80
	v_cvt_pk_bf16_f32 v102, v81, v82
	v_add_f32_e32 v80, v82, v80
	v_mfma_f32_32x32x16_bf16 v[32:47], v[198:201], v[112:115], v[32:47]
	v_exp_f32_e32 v81, v94
	v_exp_f32_e32 v82, v95
	v_add_f32_e32 v80, v81, v80
	v_cvt_pk_bf16_f32 v103, v81, v82
	v_add_f32_e32 v164, v82, v80
	v_exp_f32_e32 v64, v64
	v_exp_f32_e32 v65, v65
	v_mfma_f32_32x32x16_bf16 v[32:47], v[230:233], v[104:107], v[32:47]
	v_add_f32_e32 v165, v65, v64
	v_cvt_pk_bf16_f32 v186, v64, v65
	ds_read_b128 v[80:83], v168 offset:4608
	ds_read_b128 v[112:115], v168 offset:4640
	ds_read_b128 v[108:111], v168 offset:4672
	v_cmp_nge_f32_e64 s[8:9], s62, v164
	v_cmp_gt_f32_e32 vcc, s75, v164
	s_and_b64 s[6:7], s[6:7], vcc
	s_or_b64 s[6:7], s[6:7], s[8:9]
	ds_read_b128 v[104:107], v168 offset:4704
	s_waitcnt lgkmcnt(1)
	v_mfma_f32_32x32x16_bf16 v[80:95], v[80:83], v[148:151], 0
	ds_read_b128 v[190:193], v168 offset:9216
	ds_read_b128 v[194:197], v168 offset:9248
	ds_read_b128 v[198:201], v168 offset:13824
	ds_read_b128 v[230:233], v168 offset:13856
	v_exp_f32_e32 v64, v66
	v_exp_f32_e32 v65, v67
	v_add_f32_e32 v66, v64, v165
	v_add_f32_e32 v66, v65, v66
	v_cvt_pk_bf16_f32 v187, v64, v65
	v_mfma_f32_32x32x16_bf16 v[80:95], v[112:115], v[152:155], v[80:95]
	v_exp_f32_e32 v64, v68
	v_exp_f32_e32 v65, v69
	v_add_f32_e32 v66, v64, v66
	v_cvt_pk_bf16_f32 v188, v64, v65
	v_add_f32_e32 v64, v65, v66
	v_mfma_f32_32x32x16_bf16 v[80:95], v[108:111], v[156:159], v[80:95]
	v_exp_f32_e32 v65, v70
	v_exp_f32_e32 v66, v71
	v_add_f32_e32 v64, v65, v64
	v_cvt_pk_bf16_f32 v189, v65, v66
	v_add_f32_e32 v64, v66, v64
	s_waitcnt lgkmcnt(4)
	v_mfma_f32_32x32x16_bf16 v[80:95], v[104:107], v[160:163], v[80:95]
	v_exp_f32_e32 v65, v72
	v_exp_f32_e32 v66, v73
	v_add_f32_e32 v64, v65, v64
	v_cvt_pk_bf16_f32 v108, v65, v66
	v_add_f32_e32 v64, v66, v64
	s_waitcnt lgkmcnt(0)
	v_mfma_f32_32x32x16_bf16 v[16:31], v[190:193], v[96:99], v[16:31]
	v_exp_f32_e32 v65, v74
	v_exp_f32_e32 v66, v75
	v_add_f32_e32 v64, v65, v64
	v_cvt_pk_bf16_f32 v109, v65, v66
	v_add_f32_e32 v64, v66, v64
	v_mfma_f32_32x32x16_bf16 v[16:31], v[194:197], v[100:103], v[16:31]
	v_exp_f32_e32 v65, v76
	v_exp_f32_e32 v66, v77
	v_add_f32_e32 v64, v65, v64
	v_cvt_pk_bf16_f32 v110, v65, v66
	v_add_f32_e32 v64, v66, v64
	v_mfma_f32_32x32x16_bf16 v[0:15], v[198:201], v[96:99], v[0:15]
	v_exp_f32_e32 v65, v78
	v_exp_f32_e32 v66, v79
	v_add_f32_e32 v64, v65, v64
	v_cvt_pk_bf16_f32 v111, v65, v66
	v_add_f32_e32 v104, v66, v64
	v_exp_f32_e32 v68, v80
	v_exp_f32_e32 v69, v81
	v_mfma_f32_32x32x16_bf16 v[0:15], v[230:233], v[100:103], v[0:15]
	v_add_f32_e32 v81, v69, v68
	v_cvt_pk_bf16_f32 v80, v68, v69
	ds_read_b128 v[64:67], v168 offset:18432
	ds_read_b128 v[96:99], v168 offset:18464
	ds_read_b128 v[112:115], v168 offset:18496
	v_cmp_nge_f32_e64 s[8:9], s62, v104
	ds_read_b128 v[100:103], v168 offset:18528
	s_waitcnt lgkmcnt(1)
	v_mfma_f32_32x32x16_bf16 v[64:79], v[64:67], v[116:119], 0
	ds_read_b128 v[190:193], v168 offset:9280
	ds_read_b128 v[194:197], v168 offset:9312
	ds_read_b128 v[198:201], v168 offset:13888
	ds_read_b128 v[230:233], v168 offset:13920
	v_exp_f32_e32 v82, v82
	v_exp_f32_e32 v83, v83
	v_add_f32_e32 v81, v82, v81
	v_add_f32_e32 v105, v83, v81
	v_cvt_pk_bf16_f32 v81, v82, v83
	v_mfma_f32_32x32x16_bf16 v[64:79], v[96:99], v[120:123], v[64:79]
	v_exp_f32_e32 v82, v84
	v_exp_f32_e32 v83, v85
	v_add_f32_e32 v84, v82, v105
	v_cvt_pk_bf16_f32 v82, v82, v83
	v_add_f32_e32 v83, v83, v84
	v_mfma_f32_32x32x16_bf16 v[64:79], v[112:115], v[124:127], v[64:79]
	v_exp_f32_e32 v84, v86
	v_exp_f32_e32 v85, v87
	v_add_f32_e32 v86, v84, v83
	v_cvt_pk_bf16_f32 v83, v84, v85
	v_add_f32_e32 v84, v85, v86
	s_waitcnt lgkmcnt(4)
	v_mfma_f32_32x32x16_bf16 v[64:79], v[100:103], v[128:131], v[64:79]
	v_exp_f32_e32 v85, v88
	v_exp_f32_e32 v86, v89
	v_add_f32_e32 v87, v85, v84
	v_cvt_pk_bf16_f32 v84, v85, v86
	v_add_f32_e32 v85, v86, v87
	s_waitcnt lgkmcnt(0)
	v_mfma_f32_32x32x16_bf16 v[48:63], v[190:193], v[186:189], v[48:63]
	v_exp_f32_e32 v86, v90
	v_exp_f32_e32 v87, v91
	v_add_f32_e32 v88, v86, v85
	v_cvt_pk_bf16_f32 v85, v86, v87
	v_add_f32_e32 v86, v87, v88
	v_mfma_f32_32x32x16_bf16 v[48:63], v[194:197], v[108:111], v[48:63]
	v_exp_f32_e32 v87, v92
	v_exp_f32_e32 v88, v93
	v_add_f32_e32 v89, v87, v86
	v_cvt_pk_bf16_f32 v86, v87, v88
	v_add_f32_e32 v87, v88, v89
	v_mfma_f32_32x32x16_bf16 v[32:47], v[198:201], v[186:189], v[32:47]
	v_exp_f32_e32 v88, v94
	v_exp_f32_e32 v89, v95
	v_add_f32_e32 v90, v88, v87
	v_cvt_pk_bf16_f32 v87, v88, v89
	v_add_f32_e32 v105, v89, v90
	v_mfma_f32_32x32x16_bf16 v[32:47], v[230:233], v[108:111], v[32:47]
	ds_read_b128 v[96:99], v168 offset:18432
	ds_read_b128 v[92:95], v168 offset:18464
	ds_read_b128 v[88:91], v168 offset:18496
	v_cmp_nge_f32_e64 s[10:11], s62, v105
	s_barrier
	s_waitcnt lgkmcnt(0)
	s_cmpk_gt_u32 s33, 0xfc
	s_cbranch_scc1 .LBB0_447
	v_add_u32_e32 v100, s49, v173
	s_waitcnt vmcnt(1)
	ds_write_b128 v100, v[140:143]
	s_waitcnt vmcnt(0)
	ds_write_b128 v100, v[144:147] offset:9216

.LBB0_449:
	v_add_f32_e32 v101, v179, v164
	ds_read_b128 v[164:167], v168 offset:18528
	s_or_b64 s[4:5], s[6:7], s[4:5]
	v_add_f32_e32 v100, v178, v185
	s_or_b64 s[4:5], s[4:5], s[8:9]
	s_or_b64 s[4:5], s[4:5], s[10:11]
	v_add_f32_e32 v182, v100, v104
	v_add_f32_e32 v183, v101, v105
	s_xor_b32 s8, s48, 2
	v_exp_f32_e32 v64, v64
	v_exp_f32_e32 v65, v65
	v_mfma_f32_32x32x16_bf16 v[100:115], v[96:99], v[148:151], 0
	v_add_f32_e32 v185, v65, v64
	v_cvt_pk_bf16_f32 v64, v64, v65
	ds_read_b128 v[178:181], v168 offset:9280
	ds_read_b128 v[186:189], v168 offset:9312
	ds_read_b128 v[190:193], v168 offset:13888
	ds_read_b128 v[194:197], v168 offset:13920
	v_exp_f32_e32 v65, v66
	v_exp_f32_e32 v66, v67
	v_add_f32_e32 v67, v65, v185
	v_add_f32_e32 v67, v66, v67
	v_cvt_pk_bf16_f32 v65, v65, v66
	v_mfma_f32_32x32x16_bf16 v[100:115], v[92:95], v[152:155], v[100:115]
	v_exp_f32_e32 v66, v68
	v_exp_f32_e32 v68, v69
	v_add_f32_e32 v67, v66, v67
	v_cvt_pk_bf16_f32 v66, v66, v68
	v_add_f32_e32 v67, v68, v67
	v_mfma_f32_32x32x16_bf16 v[100:115], v[88:91], v[156:159], v[100:115]
	v_exp_f32_e32 v68, v70
	v_exp_f32_e32 v69, v71
	v_add_f32_e32 v70, v68, v67
	v_cvt_pk_bf16_f32 v67, v68, v69
	v_add_f32_e32 v68, v69, v70
	s_waitcnt lgkmcnt(4)
	v_mfma_f32_32x32x16_bf16 v[100:115], v[164:167], v[160:163], v[100:115]
	v_exp_f32_e32 v69, v72
	v_exp_f32_e32 v70, v73
	v_add_f32_e32 v71, v69, v68
	v_cvt_pk_bf16_f32 v68, v69, v70
	v_add_f32_e32 v69, v70, v71
	s_waitcnt lgkmcnt(0)
	v_mfma_f32_32x32x16_bf16 v[16:31], v[178:181], v[80:83], v[16:31]
	v_exp_f32_e32 v70, v74
	v_exp_f32_e32 v71, v75
	v_add_f32_e32 v72, v70, v69
	v_cvt_pk_bf16_f32 v69, v70, v71
	v_add_f32_e32 v70, v71, v72
	v_mfma_f32_32x32x16_bf16 v[16:31], v[186:189], v[84:87], v[16:31]
	v_exp_f32_e32 v71, v76
	v_exp_f32_e32 v72, v77
	v_add_f32_e32 v73, v71, v70
	v_cvt_pk_bf16_f32 v70, v71, v72
	v_add_f32_e32 v71, v72, v73
	v_mfma_f32_32x32x16_bf16 v[0:15], v[190:193], v[80:83], v[0:15]
	v_exp_f32_e32 v72, v78
	v_exp_f32_e32 v73, v79
	v_add_f32_e32 v74, v72, v71
	v_cvt_pk_bf16_f32 v71, v72, v73
	v_add_f32_e32 v198, v73, v74
	v_exp_f32_e32 v88, v100
	v_exp_f32_e32 v89, v101
	v_mfma_f32_32x32x16_bf16 v[0:15], v[194:197], v[84:87], v[0:15]
	v_add_f32_e32 v165, v89, v88
	v_cvt_pk_bf16_f32 v164, v88, v89
	ds_read_b128 v[72:75], v168 offset:23040
	ds_read_b128 v[76:79], v168 offset:23072
	ds_read_b128 v[80:83], v168 offset:23104
	v_cmp_nge_f32_e32 vcc, s62, v198
	ds_read_b128 v[84:87], v168 offset:23136
	v_exp_f32_e32 v166, v102
	v_exp_f32_e32 v167, v103
	s_waitcnt lgkmcnt(1)
	v_mfma_f32_32x32x16_bf16 v[88:103], v[72:75], v[116:119], 0
	ds_read_b128 v[178:181], v168 offset:27648
	ds_read_b128 v[186:189], v168 offset:27680
	ds_read_b128 v[190:193], v168 offset:32256
	ds_read_b128 v[194:197], v168 offset:32288
	v_add_f32_e32 v72, v166, v165
	v_add_f32_e32 v72, v167, v72
	v_cvt_pk_bf16_f32 v165, v166, v167
	v_mfma_f32_32x32x16_bf16 v[88:103], v[76:79], v[120:123], v[88:103]
	v_exp_f32_e32 v73, v104
	v_exp_f32_e32 v74, v105
	v_add_f32_e32 v72, v73, v72
	v_cvt_pk_bf16_f32 v166, v73, v74
	v_add_f32_e32 v72, v74, v72
	v_mfma_f32_32x32x16_bf16 v[88:103], v[80:83], v[124:127], v[88:103]
	v_exp_f32_e32 v73, v106
	v_exp_f32_e32 v74, v107
	v_add_f32_e32 v72, v73, v72
	v_cvt_pk_bf16_f32 v167, v73, v74
	v_add_f32_e32 v72, v74, v72
	s_waitcnt lgkmcnt(4)
	v_mfma_f32_32x32x16_bf16 v[88:103], v[84:87], v[128:131], v[88:103]
	v_exp_f32_e32 v73, v108
	v_exp_f32_e32 v74, v109
	v_add_f32_e32 v75, v73, v72
	v_cvt_pk_bf16_f32 v72, v73, v74
	v_add_f32_e32 v73, v74, v75
	s_waitcnt lgkmcnt(0)
	v_mfma_f32_32x32x16_bf16 v[48:63], v[178:181], v[64:67], v[48:63]
	v_exp_f32_e32 v74, v110
	v_exp_f32_e32 v75, v111
	v_add_f32_e32 v76, v74, v73
	v_cvt_pk_bf16_f32 v73, v74, v75
	v_add_f32_e32 v74, v75, v76
	v_mfma_f32_32x32x16_bf16 v[48:63], v[186:189], v[68:71], v[48:63]
	v_exp_f32_e32 v75, v112
	v_exp_f32_e32 v76, v113
	v_add_f32_e32 v77, v75, v74
	v_cvt_pk_bf16_f32 v74, v75, v76
	v_add_f32_e32 v75, v76, v77
	v_mfma_f32_32x32x16_bf16 v[32:47], v[190:193], v[64:67], v[32:47]
	v_exp_f32_e32 v76, v114
	v_exp_f32_e32 v77, v115
	v_add_f32_e32 v78, v76, v75
	v_cvt_pk_bf16_f32 v75, v76, v77
	v_add_f32_e32 v199, v77, v78
	v_exp_f32_e32 v76, v88
	v_exp_f32_e32 v77, v89
	v_mfma_f32_32x32x16_bf16 v[32:47], v[194:197], v[68:71], v[32:47]
	v_add_f32_e32 v113, v77, v76
	v_cvt_pk_bf16_f32 v112, v76, v77
	ds_read_b128 v[64:67], v168 offset:23040
	ds_read_b128 v[104:107], v168 offset:23072
	ds_read_b128 v[108:111], v168 offset:23104
	s_or_b64 s[6:7], s[4:5], vcc
	v_cmp_nge_f32_e32 vcc, s62, v199
	v_add_f32_e32 v182, v182, v198
	v_add_f32_e32 v183, v183, v199
	ds_read_b128 v[68:71], v168 offset:23136
	v_exp_f32_e32 v114, v90
	v_exp_f32_e32 v115, v91
	s_waitcnt lgkmcnt(1)
; template <int MODE, bool FAST> __device__ __forceinline__ bool attn_unit(LAS unsigned char* lds, const AttU& U, const int wv) {
;     ...
;         for (int t2 = U.kt0; t2 < U.kt1; t2 += 2) { ATT_TILE(t2, 4, rk, rr, rv); ATT_TILE(t2 + 1, 4, rk2, rr2, rv2); }
	v_mfma_f32_32x32x16_bf16 v[76:91], v[64:67], v[148:151], 0
	ds_read_b128 v[178:181], v168 offset:27648
	ds_read_b128 v[186:189], v168 offset:27680
	ds_read_b128 v[190:193], v168 offset:32256
	ds_read_b128 v[194:197], v168 offset:32288
	v_add_f32_e32 v64, v114, v113
	v_add_f32_e32 v64, v115, v64
	v_cvt_pk_bf16_f32 v113, v114, v115
	v_mfma_f32_32x32x16_bf16 v[76:91], v[104:107], v[152:155], v[76:91]
	v_exp_f32_e32 v65, v92
	v_exp_f32_e32 v66, v93
	v_add_f32_e32 v64, v65, v64
	v_cvt_pk_bf16_f32 v114, v65, v66
	v_add_f32_e32 v64, v66, v64
	v_mfma_f32_32x32x16_bf16 v[76:91], v[108:111], v[156:159], v[76:91]
	v_exp_f32_e32 v65, v94
	v_exp_f32_e32 v66, v95
	v_add_f32_e32 v64, v65, v64
	v_cvt_pk_bf16_f32 v115, v65, v66
	v_add_f32_e32 v64, v66, v64
	s_waitcnt lgkmcnt(4)
	v_mfma_f32_32x32x16_bf16 v[76:91], v[68:71], v[160:163], v[76:91]
	v_exp_f32_e32 v65, v96
	v_exp_f32_e32 v66, v97
	v_add_f32_e32 v64, v65, v64
	v_cvt_pk_bf16_f32 v92, v65, v66
	v_add_f32_e32 v64, v66, v64
	s_waitcnt lgkmcnt(0)
	v_mfma_f32_32x32x16_bf16 v[16:31], v[178:181], v[164:167], v[16:31]
	v_exp_f32_e32 v65, v98
	v_exp_f32_e32 v66, v99
	v_add_f32_e32 v64, v65, v64
	v_cvt_pk_bf16_f32 v93, v65, v66
	v_add_f32_e32 v64, v66, v64
	v_mfma_f32_32x32x16_bf16 v[16:31], v[186:189], v[72:75], v[16:31]
	v_exp_f32_e32 v65, v100
	v_exp_f32_e32 v66, v101
	v_add_f32_e32 v64, v65, v64
	v_cvt_pk_bf16_f32 v94, v65, v66
	v_add_f32_e32 v64, v66, v64
	v_mfma_f32_32x32x16_bf16 v[0:15], v[190:193], v[164:167], v[0:15]
	v_exp_f32_e32 v65, v102
	v_exp_f32_e32 v66, v103
	v_add_f32_e32 v64, v65, v64
	v_cvt_pk_bf16_f32 v95, v65, v66
	v_add_f32_e32 v198, v66, v64
	s_mulk_i32 s8, 0x4800
	v_exp_f32_e32 v68, v76
	v_exp_f32_e32 v69, v77
	v_mfma_f32_32x32x16_bf16 v[0:15], v[194:197], v[72:75], v[0:15]
	v_add_f32_e32 v97, v69, v68
	v_cvt_pk_bf16_f32 v96, v68, v69
	v_add_u32_e32 v185, s8, v184
	ds_read_b128 v[64:67], v185
	ds_read_b128 v[100:103], v185 offset:32
	ds_read_b128 v[104:107], v185 offset:64
	v_cmp_nge_f32_e64 s[4:5], s62, v198
	ds_read_b128 v[108:111], v185 offset:96
	s_or_b64 s[6:7], s[6:7], vcc
	v_exp_f32_e32 v98, v78
	v_exp_f32_e32 v99, v79
	s_waitcnt lgkmcnt(1)
	v_mfma_f32_32x32x16_bf16 v[64:79], v[64:67], v[116:119], 0
	ds_read_b128 v[164:167], v168 offset:27712
	ds_read_b128 v[178:181], v168 offset:27744
	ds_read_b128 v[186:189], v168 offset:32320
	ds_read_b128 v[190:193], v168 offset:32352
	v_add_f32_e32 v97, v98, v97
	v_add_f32_e32 v168, v99, v97
	v_cvt_pk_bf16_f32 v97, v98, v99
	v_mfma_f32_32x32x16_bf16 v[64:79], v[100:103], v[120:123], v[64:79]
	v_exp_f32_e32 v80, v80
	v_exp_f32_e32 v81, v81
	v_add_f32_e32 v99, v80, v168
	v_cvt_pk_bf16_f32 v98, v80, v81
	v_add_f32_e32 v80, v81, v99
	v_mfma_f32_32x32x16_bf16 v[64:79], v[104:107], v[124:127], v[64:79]
	v_exp_f32_e32 v81, v82
	v_exp_f32_e32 v82, v83
	v_add_f32_e32 v80, v81, v80
	v_cvt_pk_bf16_f32 v99, v81, v82
	v_add_f32_e32 v80, v82, v80
	s_waitcnt lgkmcnt(4)
	v_mfma_f32_32x32x16_bf16 v[64:79], v[108:111], v[128:131], v[64:79]
	v_exp_f32_e32 v81, v84
	v_exp_f32_e32 v82, v85
	v_add_f32_e32 v80, v81, v80
	v_cvt_pk_bf16_f32 v100, v81, v82
	v_add_f32_e32 v80, v82, v80
	s_waitcnt lgkmcnt(0)
	v_mfma_f32_32x32x16_bf16 v[48:63], v[164:167], v[112:115], v[48:63]
	v_exp_f32_e32 v81, v86
	v_exp_f32_e32 v82, v87
	v_add_f32_e32 v80, v81, v80
	v_cvt_pk_bf16_f32 v101, v81, v82
	v_add_f32_e32 v80, v82, v80
	v_mfma_f32_32x32x16_bf16 v[48:63], v[178:181], v[92:95], v[48:63]
	v_exp_f32_e32 v81, v88
	v_exp_f32_e32 v82, v89
	v_add_f32_e32 v80, v81, v80
	v_cvt_pk_bf16_f32 v102, v81, v82
	v_add_f32_e32 v80, v82, v80
	v_mfma_f32_32x32x16_bf16 v[32:47], v[186:189], v[112:115], v[32:47]
	v_exp_f32_e32 v81, v90
	v_exp_f32_e32 v82, v91
	v_add_f32_e32 v80, v81, v80
	v_cvt_pk_bf16_f32 v103, v81, v82
	v_add_f32_e32 v199, v82, v80
	v_mfma_f32_32x32x16_bf16 v[32:47], v[190:193], v[92:95], v[32:47]
	ds_read_b128 v[80:83], v185
	ds_read_b128 v[108:111], v185 offset:32
	ds_read_b128 v[104:107], v185 offset:64
	s_or_b64 s[4:5], s[6:7], s[4:5]
	v_cmp_nge_f32_e32 vcc, s62, v199
	s_or_b64 s[4:5], s[4:5], vcc
	s_cmp_lg_u64 s[4:5], 0
	s_cselect_b64 s[4:5], -1, 0
	s_or_b64 s[42:43], s[42:43], s[4:5]
	v_add_f32_e32 v178, v182, v198
	v_add_f32_e32 v179, v183, v199
	s_barrier
	s_waitcnt lgkmcnt(0)
	s_add_u32 s46, s46, 0x8000
	s_addc_u32 s47, s47, 0
	s_and_b64 vcc, exec, s[44:45]
	s_cbranch_vccnz .LBB0_451
	s_mov_b32 s33, s14
	s_branch .LBB0_437

.LBB0_927:
	s_add_i32 s6, s61, -1
	s_and_b32 s77, s61, 2
	s_and_b32 s79, s6, 3
	s_cmp_eq_u32 s61, 0
	s_cselect_b64 s[8:9], -1, 0
	s_mulk_i32 s79, 0x5800
	s_and_b64 s[6:7], s[8:9], exec
	s_mul_i32 s78, s77, 0x5800
	s_cselect_b32 s6, 0, s79
	s_add_i32 s76, s78, 0
	v_add_u32_e32 v199, s76, v241
	v_exp_f32_e32 v64, v64
	v_exp_f32_e32 v65, v65
	v_add_u32_e32 v210, s6, v244
	v_add_f32_e32 v84, v65, v64
	v_cvt_pk_bf16_f32 v178, v64, v65
	v_exp_f32_e32 v64, v66
	ds_read_b128 v[182:185], v199 offset:96
	ds_read_b128 v[246:249], v199 offset:128
	ds_read_b128 v[250:253], v199 offset:160
	v_exp_f32_e32 v65, v67
	v_add_f32_e32 v66, v64, v84
	v_mfma_f32_32x32x16_bf16 v[80:95], v[80:83], v[122:125], 0
	v_add_f32_e32 v66, v65, v66
	v_cvt_pk_bf16_f32 v179, v64, v65
	v_mfma_f32_32x32x16_bf16 v[80:95], v[174:177], v[126:129], v[80:95]
	v_exp_f32_e32 v64, v68
	v_exp_f32_e32 v65, v69
	v_add_f32_e32 v66, v64, v66
	v_add_f32_e32 v66, v65, v66
	v_cvt_pk_bf16_f32 v180, v64, v65
	v_mfma_f32_32x32x16_bf16 v[80:95], v[170:173], v[130:133], v[80:95]
	v_exp_f32_e32 v64, v70
	v_exp_f32_e32 v65, v71
	v_add_f32_e32 v66, v64, v66
	v_add_f32_e32 v170, v65, v66
	v_cvt_pk_bf16_f32 v181, v64, v65
	s_waitcnt lgkmcnt(0)
	v_mfma_f32_32x32x16_bf16 v[80:95], v[182:185], v[134:137], v[80:95]
	ds_read_b128 v[64:67], v210 offset:13376
	ds_read_b128 v[68:71], v210 offset:13408
	ds_read_b128 v[174:177], v210 offset:17984
	ds_read_b128 v[218:221], v210 offset:18016
	v_exp_f32_e32 v72, v72
	v_exp_f32_e32 v73, v73
	v_add_f32_e32 v170, v72, v170
	v_add_f32_e32 v171, v73, v170
	v_cvt_pk_bf16_f32 v170, v72, v73
	v_mfma_f32_32x32x16_bf16 v[80:95], v[246:249], v[154:157], v[80:95]
	v_exp_f32_e32 v72, v74
	v_exp_f32_e32 v73, v75
	v_add_f32_e32 v74, v72, v171
	v_add_f32_e32 v74, v73, v74
	v_cvt_pk_bf16_f32 v171, v72, v73
	v_mfma_f32_32x32x16_bf16 v[80:95], v[250:253], v[158:161], v[80:95]
	v_exp_f32_e32 v72, v76
	v_exp_f32_e32 v73, v77
	v_add_f32_e32 v74, v72, v74
	v_add_f32_e32 v74, v73, v74
	v_cvt_pk_bf16_f32 v172, v72, v73
	s_waitcnt lgkmcnt(0)
	v_mfma_f32_32x32x16_bf16 v[16:31], v[64:67], v[162:165], v[16:31]
	v_exp_f32_e32 v64, v78
	v_exp_f32_e32 v65, v79
	v_add_f32_e32 v66, v64, v74
	v_add_f32_e32 v246, v65, v66
	v_cvt_pk_bf16_f32 v173, v64, v65
	v_mfma_f32_32x32x16_bf16 v[0:15], v[174:177], v[162:165], v[0:15]
	ds_read_b128 v[64:67], v199 offset:6656
	ds_read_b128 v[182:185], v199 offset:6688
	ds_read_b128 v[174:177], v199 offset:6720
	v_cmp_nge_f32_e64 s[6:7], s48, v246
	v_cmp_gt_f32_e32 vcc, s49, v246
	v_mfma_f32_32x32x16_bf16 v[16:31], v[68:71], v[166:169], v[16:31]
	v_exp_f32_e32 v68, v80
	v_exp_f32_e32 v69, v81
	v_exp_f32_e32 v80, v82
	v_add_f32_e32 v70, v69, v68
	v_cvt_pk_bf16_f32 v162, v68, v69
	v_exp_f32_e32 v81, v83
	v_add_f32_e32 v82, v80, v70
	v_mfma_f32_32x32x16_bf16 v[0:15], v[218:221], v[166:169], v[0:15]
	s_and_b64 vcc, s[8:9], vcc
	s_or_b64 s[6:7], s[6:7], vcc
	v_add_u32_e32 v211, s76, v243
	ds_read_b128 v[166:169], v199 offset:6752
	ds_read_b128 v[218:221], v199 offset:6784
	ds_read_b128 v[248:251], v199 offset:6816
	s_waitcnt lgkmcnt(3)
	v_mfma_f32_32x32x16_bf16 v[64:79], v[64:67], v[98:101], 0
	v_add_f32_e32 v82, v81, v82
	v_cvt_pk_bf16_f32 v163, v80, v81
	v_mfma_f32_32x32x16_bf16 v[64:79], v[182:185], v[102:105], v[64:79]
	v_exp_f32_e32 v80, v84
	v_exp_f32_e32 v81, v85
	v_add_f32_e32 v82, v80, v82
	v_add_f32_e32 v82, v81, v82
	v_cvt_pk_bf16_f32 v164, v80, v81
	v_mfma_f32_32x32x16_bf16 v[64:79], v[174:177], v[106:109], v[64:79]
	v_exp_f32_e32 v80, v86
	v_exp_f32_e32 v81, v87
	v_add_f32_e32 v82, v80, v82
	v_add_f32_e32 v174, v81, v82
	v_cvt_pk_bf16_f32 v165, v80, v81
	s_waitcnt lgkmcnt(0)
	v_mfma_f32_32x32x16_bf16 v[64:79], v[166:169], v[110:113], v[64:79]
	ds_read_b128 v[80:83], v211 offset:13312
	ds_read_b128 v[84:87], v211 offset:13344
	ds_read_b128 v[182:185], v211 offset:17920
	ds_read_b128 v[222:225], v211 offset:17952
	v_exp_f32_e32 v88, v88
	v_exp_f32_e32 v89, v89
	v_add_f32_e32 v166, v88, v174
	v_add_f32_e32 v166, v89, v166
	v_cvt_pk_bf16_f32 v174, v88, v89
	v_mfma_f32_32x32x16_bf16 v[64:79], v[218:221], v[114:117], v[64:79]
	v_exp_f32_e32 v88, v90
	v_exp_f32_e32 v89, v91
	v_add_f32_e32 v90, v88, v166
	v_add_f32_e32 v90, v89, v90
	v_cvt_pk_bf16_f32 v175, v88, v89
	v_mfma_f32_32x32x16_bf16 v[64:79], v[248:251], v[118:121], v[64:79]
	v_exp_f32_e32 v88, v92
	v_exp_f32_e32 v89, v93
	v_add_f32_e32 v90, v88, v90
	v_add_f32_e32 v90, v89, v90
	v_cvt_pk_bf16_f32 v176, v88, v89
	s_waitcnt lgkmcnt(0)
	v_mfma_f32_32x32x16_bf16 v[48:63], v[80:83], v[178:181], v[48:63]
	v_exp_f32_e32 v80, v94
	v_exp_f32_e32 v81, v95
	v_add_f32_e32 v82, v80, v90
	v_add_f32_e32 v247, v81, v82
	v_cvt_pk_bf16_f32 v177, v80, v81
	v_mfma_f32_32x32x16_bf16 v[32:47], v[182:185], v[178:181], v[32:47]
	ds_read_b128 v[80:83], v199 offset:6656
	ds_read_b128 v[182:185], v199 offset:6688
	ds_read_b128 v[178:181], v199 offset:6720
	v_cmp_nge_f32_e64 s[10:11], s48, v247
	v_cmp_gt_f32_e32 vcc, s49, v247
	v_mfma_f32_32x32x16_bf16 v[48:63], v[84:87], v[170:173], v[48:63]
	v_exp_f32_e32 v64, v64
	v_exp_f32_e32 v65, v65
	s_nop 0
	v_add_f32_e32 v84, v65, v64
	v_cvt_pk_bf16_f32 v166, v64, v65
	v_exp_f32_e32 v64, v66
	v_exp_f32_e32 v65, v67
	v_add_f32_e32 v66, v64, v84
	v_mfma_f32_32x32x16_bf16 v[32:47], v[222:225], v[170:173], v[32:47]
	s_and_b64 s[8:9], s[8:9], vcc
	s_or_b64 s[8:9], s[8:9], s[10:11]
	ds_read_b128 v[170:173], v199 offset:6752
	ds_read_b128 v[218:221], v199 offset:6784
	ds_read_b128 v[222:225], v199 offset:6816
	s_waitcnt lgkmcnt(3)
	v_mfma_f32_32x32x16_bf16 v[80:95], v[80:83], v[122:125], 0
	v_add_f32_e32 v66, v65, v66
	v_cvt_pk_bf16_f32 v167, v64, v65
	v_mfma_f32_32x32x16_bf16 v[80:95], v[182:185], v[126:129], v[80:95]
	v_exp_f32_e32 v64, v68
	v_exp_f32_e32 v65, v69
	v_add_f32_e32 v66, v64, v66
	v_add_f32_e32 v66, v65, v66
	v_cvt_pk_bf16_f32 v168, v64, v65
	v_mfma_f32_32x32x16_bf16 v[80:95], v[178:181], v[130:133], v[80:95]
	v_exp_f32_e32 v64, v70
	v_exp_f32_e32 v65, v71
	v_add_f32_e32 v66, v64, v66
	v_add_f32_e32 v178, v65, v66
	v_cvt_pk_bf16_f32 v169, v64, v65
	s_waitcnt lgkmcnt(0)
	v_mfma_f32_32x32x16_bf16 v[80:95], v[170:173], v[134:137], v[80:95]
	ds_read_b128 v[64:67], v211 offset:13312
	ds_read_b128 v[68:71], v211 offset:13344
	ds_read_b128 v[182:185], v211 offset:17920
	ds_read_b128 v[248:251], v211 offset:17952
	v_exp_f32_e32 v72, v72
	v_exp_f32_e32 v73, v73
	v_add_f32_e32 v170, v72, v178
	v_add_f32_e32 v170, v73, v170
	v_cvt_pk_bf16_f32 v178, v72, v73
	v_mfma_f32_32x32x16_bf16 v[80:95], v[218:221], v[154:157], v[80:95]
	v_exp_f32_e32 v72, v74
	v_exp_f32_e32 v73, v75
	v_add_f32_e32 v74, v72, v170
	v_add_f32_e32 v74, v73, v74
	v_cvt_pk_bf16_f32 v179, v72, v73
	v_mfma_f32_32x32x16_bf16 v[80:95], v[222:225], v[158:161], v[80:95]
	v_exp_f32_e32 v72, v76
	v_exp_f32_e32 v73, v77
	v_add_f32_e32 v74, v72, v74
	v_add_f32_e32 v74, v73, v74
	v_cvt_pk_bf16_f32 v180, v72, v73
	s_waitcnt lgkmcnt(0)
	v_mfma_f32_32x32x16_bf16 v[16:31], v[64:67], v[162:165], v[16:31]
	v_exp_f32_e32 v64, v78
	v_exp_f32_e32 v65, v79
	v_add_f32_e32 v66, v64, v74
	v_add_f32_e32 v210, v65, v66
	v_cvt_pk_bf16_f32 v181, v64, v65
	v_mfma_f32_32x32x16_bf16 v[0:15], v[182:185], v[162:165], v[0:15]
	v_add_u32_e32 v226, s78, v242
	ds_read_b128 v[64:67], v226 offset:22528
	ds_read_b128 v[170:173], v226 offset:22560
	ds_read_b128 v[182:185], v226 offset:22592
	v_cmp_nge_f32_e64 s[10:11], s48, v210
	v_mfma_f32_32x32x16_bf16 v[16:31], v[68:71], v[174:177], v[16:31]
	v_exp_f32_e32 v68, v80
	v_exp_f32_e32 v69, v81
	v_exp_f32_e32 v80, v82
	v_add_f32_e32 v70, v69, v68
	v_cvt_pk_bf16_f32 v162, v68, v69
	v_exp_f32_e32 v81, v83
	v_add_f32_e32 v82, v80, v70
	v_mfma_f32_32x32x16_bf16 v[0:15], v[248:251], v[174:177], v[0:15]
	ds_read_b128 v[174:177], v226 offset:22624
	ds_read_b128 v[218:221], v226 offset:22656
	ds_read_b128 v[222:225], v226 offset:22688
	s_waitcnt lgkmcnt(3)
	v_mfma_f32_32x32x16_bf16 v[64:79], v[64:67], v[98:101], 0
	v_add_f32_e32 v82, v81, v82
	v_cvt_pk_bf16_f32 v163, v80, v81
	v_mfma_f32_32x32x16_bf16 v[64:79], v[170:173], v[102:105], v[64:79]
	v_exp_f32_e32 v80, v84
	v_exp_f32_e32 v81, v85
	v_add_f32_e32 v82, v80, v82
	v_add_f32_e32 v82, v81, v82
	v_cvt_pk_bf16_f32 v164, v80, v81
	v_mfma_f32_32x32x16_bf16 v[64:79], v[182:185], v[106:109], v[64:79]
	v_exp_f32_e32 v80, v86
	v_exp_f32_e32 v81, v87
	v_add_f32_e32 v82, v80, v82
	v_add_f32_e32 v170, v81, v82
	v_cvt_pk_bf16_f32 v165, v80, v81
	s_waitcnt lgkmcnt(0)
	v_mfma_f32_32x32x16_bf16 v[64:79], v[174:177], v[110:113], v[64:79]
	ds_read_b128 v[80:83], v211 offset:13376
	ds_read_b128 v[84:87], v211 offset:13408
	ds_read_b128 v[182:185], v211 offset:17984
	ds_read_b128 v[248:251], v211 offset:18016
	v_exp_f32_e32 v88, v88
	v_exp_f32_e32 v89, v89
	v_add_f32_e32 v170, v88, v170
	v_add_f32_e32 v171, v89, v170
	v_cvt_pk_bf16_f32 v170, v88, v89
	v_mfma_f32_32x32x16_bf16 v[64:79], v[218:221], v[114:117], v[64:79]
	v_exp_f32_e32 v88, v90
	v_exp_f32_e32 v89, v91
	v_add_f32_e32 v90, v88, v171
	v_add_f32_e32 v90, v89, v90
	v_cvt_pk_bf16_f32 v171, v88, v89
	v_mfma_f32_32x32x16_bf16 v[64:79], v[222:225], v[118:121], v[64:79]
	v_exp_f32_e32 v88, v92
	v_exp_f32_e32 v89, v93
	v_add_f32_e32 v90, v88, v90
	v_add_f32_e32 v90, v89, v90
	v_cvt_pk_bf16_f32 v172, v88, v89
	s_waitcnt lgkmcnt(0)
	v_mfma_f32_32x32x16_bf16 v[48:63], v[80:83], v[166:169], v[48:63]
	v_exp_f32_e32 v80, v94
	v_exp_f32_e32 v81, v95
	v_add_f32_e32 v82, v80, v90
	v_add_f32_e32 v211, v81, v82
	v_cvt_pk_bf16_f32 v173, v80, v81
	v_mfma_f32_32x32x16_bf16 v[32:47], v[182:185], v[166:169], v[32:47]
	ds_read_b128 v[80:83], v226 offset:22528
	ds_read_b128 v[182:185], v226 offset:22560
	ds_read_b128 v[174:177], v226 offset:22592
	v_cmp_nge_f32_e64 s[12:13], s48, v211
	v_mfma_f32_32x32x16_bf16 v[48:63], v[84:87], v[178:181], v[48:63]
	s_barrier
	s_waitcnt lgkmcnt(0)
	v_mfma_f32_32x32x16_bf16 v[32:47], v[248:251], v[178:181], v[32:47]
	s_cmpk_gt_u32 s61, 0xfc
	s_cbranch_scc1 .LBB0_933
	s_add_i32 s24, s79, 0
	v_add_u32_e32 v84, s24, v238
	v_add_u32_e32 v85, s24, v245
	v_add_u32_e32 v86, s24, v198
	s_waitcnt vmcnt(1)
	ds_write_b128 v84, v[150:153]
	s_waitcnt vmcnt(0)
	ds_write_b64 v85, v[190:191] offset:128
	ds_write_b128 v86, v[138:141] offset:13312

.LBB0_935:
	s_or_b64 s[6:7], s[8:9], s[6:7]
	v_add_f32_e32 v84, v204, v246
	v_add_f32_e32 v85, v205, v247
	s_or_b64 s[6:7], s[6:7], s[10:11]
	s_or_b64 s[6:7], s[6:7], s[12:13]
	v_add_f32_e32 v178, v84, v210
	v_add_f32_e32 v179, v85, v211
	s_xor_b32 s10, s77, 2
	v_exp_f32_e32 v64, v64
	v_exp_f32_e32 v65, v65
	v_add_u32_e32 v222, s78, v244
	v_add_f32_e32 v84, v65, v64
	v_cvt_pk_bf16_f32 v166, v64, v65
	v_exp_f32_e32 v64, v66
	ds_read_b128 v[204:207], v199 offset:22624
	ds_read_b128 v[208:211], v199 offset:22656
	ds_read_b128 v[218:221], v199 offset:22688
	v_exp_f32_e32 v65, v67
	v_add_f32_e32 v66, v64, v84
	v_mfma_f32_32x32x16_bf16 v[80:95], v[80:83], v[122:125], 0
	v_add_f32_e32 v66, v65, v66
	v_cvt_pk_bf16_f32 v167, v64, v65
	v_mfma_f32_32x32x16_bf16 v[80:95], v[182:185], v[126:129], v[80:95]
	v_exp_f32_e32 v64, v68
	v_exp_f32_e32 v65, v69
	v_add_f32_e32 v66, v64, v66
	v_add_f32_e32 v66, v65, v66
	v_cvt_pk_bf16_f32 v168, v64, v65
	v_mfma_f32_32x32x16_bf16 v[80:95], v[174:177], v[130:133], v[80:95]
	v_exp_f32_e32 v64, v70
	v_exp_f32_e32 v65, v71
	v_add_f32_e32 v66, v64, v66
	v_add_f32_e32 v174, v65, v66
	v_cvt_pk_bf16_f32 v169, v64, v65
	s_waitcnt lgkmcnt(0)
	v_mfma_f32_32x32x16_bf16 v[80:95], v[204:207], v[134:137], v[80:95]
	ds_read_b128 v[64:67], v222 offset:13376
	ds_read_b128 v[68:71], v222 offset:13408
	ds_read_b128 v[180:183], v222 offset:17984
	ds_read_b128 v[222:225], v222 offset:18016
	v_exp_f32_e32 v72, v72
	v_exp_f32_e32 v73, v73
	v_add_f32_e32 v174, v72, v174
	v_add_f32_e32 v175, v73, v174
	v_cvt_pk_bf16_f32 v174, v72, v73
	v_mfma_f32_32x32x16_bf16 v[80:95], v[208:211], v[154:157], v[80:95]
	v_exp_f32_e32 v72, v74
	v_exp_f32_e32 v73, v75
	v_add_f32_e32 v74, v72, v175
	v_add_f32_e32 v74, v73, v74
	v_cvt_pk_bf16_f32 v175, v72, v73
	v_mfma_f32_32x32x16_bf16 v[80:95], v[218:221], v[158:161], v[80:95]
	v_exp_f32_e32 v72, v76
	v_exp_f32_e32 v73, v77
	v_add_f32_e32 v74, v72, v74
	v_add_f32_e32 v74, v73, v74
	v_cvt_pk_bf16_f32 v176, v72, v73
	s_waitcnt lgkmcnt(0)
	v_mfma_f32_32x32x16_bf16 v[16:31], v[64:67], v[162:165], v[16:31]
	v_exp_f32_e32 v64, v78
	v_exp_f32_e32 v65, v79
	v_add_f32_e32 v66, v64, v74
	v_add_f32_e32 v204, v65, v66
	v_cvt_pk_bf16_f32 v177, v64, v65
	v_mfma_f32_32x32x16_bf16 v[0:15], v[180:183], v[162:165], v[0:15]
	ds_read_b128 v[64:67], v199 offset:29184
	ds_read_b128 v[180:183], v199 offset:29216
	ds_read_b128 v[208:211], v199 offset:29248
	v_cmp_nge_f32_e32 vcc, s48, v204
	v_mfma_f32_32x32x16_bf16 v[16:31], v[68:71], v[170:173], v[16:31]
	v_mfma_f32_32x32x16_bf16 v[0:15], v[222:225], v[170:173], v[0:15]
	v_mad_u32_u24 v68, v187, s69, v186
	v_add_u32_e32 v206, s76, v68
	v_exp_f32_e32 v68, v80
	v_exp_f32_e32 v69, v81
	v_exp_f32_e32 v80, v82
	v_add_f32_e32 v70, v69, v68
	v_cvt_pk_bf16_f32 v162, v68, v69
	ds_read_b128 v[170:173], v199 offset:29280
	ds_read_b128 v[218:221], v199 offset:29312
	ds_read_b128 v[222:225], v199 offset:29344
	v_exp_f32_e32 v81, v83
	v_add_f32_e32 v82, v80, v70
	s_waitcnt lgkmcnt(3)
	v_mfma_f32_32x32x16_bf16 v[64:79], v[64:67], v[98:101], 0
	v_add_f32_e32 v82, v81, v82
	v_cvt_pk_bf16_f32 v163, v80, v81
	v_mfma_f32_32x32x16_bf16 v[64:79], v[180:183], v[102:105], v[64:79]
	v_exp_f32_e32 v80, v84
	v_exp_f32_e32 v81, v85
	v_add_f32_e32 v82, v80, v82
	v_add_f32_e32 v82, v81, v82
	v_cvt_pk_bf16_f32 v164, v80, v81
	v_mfma_f32_32x32x16_bf16 v[64:79], v[208:211], v[106:109], v[64:79]
	v_exp_f32_e32 v80, v86
	v_exp_f32_e32 v81, v87
	v_add_f32_e32 v82, v80, v82
	v_add_f32_e32 v184, v81, v82
	v_cvt_pk_bf16_f32 v165, v80, v81
	s_waitcnt lgkmcnt(0)
	v_mfma_f32_32x32x16_bf16 v[64:79], v[170:173], v[110:113], v[64:79]
	ds_read_b128 v[80:83], v206 offset:35840
	ds_read_b128 v[84:87], v206 offset:35872
	ds_read_b128 v[180:183], v206 offset:40448
	ds_read_b128 v[208:211], v206 offset:40480
	v_exp_f32_e32 v88, v88
	v_exp_f32_e32 v89, v89
	v_add_f32_e32 v170, v88, v184
	v_add_f32_e32 v171, v89, v170
	v_cvt_pk_bf16_f32 v170, v88, v89
	v_mfma_f32_32x32x16_bf16 v[64:79], v[218:221], v[114:117], v[64:79]
	v_exp_f32_e32 v88, v90
	v_exp_f32_e32 v89, v91
	v_add_f32_e32 v90, v88, v171
	v_add_f32_e32 v90, v89, v90
	v_cvt_pk_bf16_f32 v171, v88, v89
	v_mfma_f32_32x32x16_bf16 v[64:79], v[222:225], v[118:121], v[64:79]
	v_exp_f32_e32 v88, v92
	v_exp_f32_e32 v89, v93
	v_add_f32_e32 v90, v88, v90
	v_add_f32_e32 v90, v89, v90
	v_cvt_pk_bf16_f32 v172, v88, v89
	s_waitcnt lgkmcnt(0)
	v_mfma_f32_32x32x16_bf16 v[48:63], v[80:83], v[166:169], v[48:63]
	v_exp_f32_e32 v80, v94
	v_exp_f32_e32 v81, v95
	v_add_f32_e32 v82, v80, v90
	v_add_f32_e32 v205, v81, v82
	v_cvt_pk_bf16_f32 v173, v80, v81
	v_mfma_f32_32x32x16_bf16 v[32:47], v[180:183], v[166:169], v[32:47]
	ds_read_b128 v[80:83], v199 offset:29184
	ds_read_b128 v[166:169], v199 offset:29216
	ds_read_b128 v[182:185], v199 offset:29248
	s_or_b64 s[8:9], s[6:7], vcc
	v_cmp_nge_f32_e32 vcc, s48, v205
	v_add_f32_e32 v204, v178, v204
	v_add_f32_e32 v205, v179, v205
	v_mfma_f32_32x32x16_bf16 v[48:63], v[84:87], v[174:177], v[48:63]
	v_exp_f32_e32 v64, v64
	v_exp_f32_e32 v65, v65
	s_nop 0
	v_add_f32_e32 v84, v65, v64
	v_cvt_pk_bf16_f32 v178, v64, v65
	v_exp_f32_e32 v64, v66
	v_exp_f32_e32 v65, v67
	v_add_f32_e32 v66, v64, v84
	v_mfma_f32_32x32x16_bf16 v[32:47], v[208:211], v[174:177], v[32:47]
	ds_read_b128 v[174:177], v199 offset:29280
	ds_read_b128 v[208:211], v199 offset:29312
	ds_read_b128 v[218:221], v199 offset:29344
	s_waitcnt lgkmcnt(3)
; template <int MODE, bool FAST> __device__ __forceinline__ bool attn_unit(LAS unsigned char* lds, const AttU& U, const int wv) {
;     ...
;         for (int t2 = U.kt0; t2 < U.kt1; t2 += 2) { ATT_TILE(t2, 4, rk, rr, rv); ATT_TILE(t2 + 1, 4, rk2, rr2, rv2); }
	v_mfma_f32_32x32x16_bf16 v[80:95], v[80:83], v[122:125], 0
	v_add_f32_e32 v66, v65, v66
	v_cvt_pk_bf16_f32 v179, v64, v65
	v_mfma_f32_32x32x16_bf16 v[80:95], v[166:169], v[126:129], v[80:95]
	v_exp_f32_e32 v64, v68
	v_exp_f32_e32 v65, v69
	v_add_f32_e32 v66, v64, v66
	v_add_f32_e32 v66, v65, v66
	v_cvt_pk_bf16_f32 v180, v64, v65
	v_mfma_f32_32x32x16_bf16 v[80:95], v[182:185], v[130:133], v[80:95]
	v_exp_f32_e32 v64, v70
	v_exp_f32_e32 v65, v71
	v_add_f32_e32 v66, v64, v66
	v_add_f32_e32 v182, v65, v66
	v_cvt_pk_bf16_f32 v181, v64, v65
	s_waitcnt lgkmcnt(0)
	v_mfma_f32_32x32x16_bf16 v[80:95], v[174:177], v[134:137], v[80:95]
	ds_read_b128 v[64:67], v206 offset:35840
	ds_read_b128 v[68:71], v206 offset:35872
	ds_read_b128 v[166:169], v206 offset:40448
	ds_read_b128 v[222:225], v206 offset:40480
	v_exp_f32_e32 v72, v72
	v_exp_f32_e32 v73, v73
	v_add_f32_e32 v174, v72, v182
	v_add_f32_e32 v174, v73, v174
	v_cvt_pk_bf16_f32 v182, v72, v73
	v_mfma_f32_32x32x16_bf16 v[80:95], v[208:211], v[154:157], v[80:95]
	v_exp_f32_e32 v72, v74
	v_exp_f32_e32 v73, v75
	v_add_f32_e32 v74, v72, v174
	v_add_f32_e32 v74, v73, v74
	v_cvt_pk_bf16_f32 v183, v72, v73
	v_mfma_f32_32x32x16_bf16 v[80:95], v[218:221], v[158:161], v[80:95]
	v_exp_f32_e32 v72, v76
	v_exp_f32_e32 v73, v77
	v_add_f32_e32 v74, v72, v74
	v_add_f32_e32 v74, v73, v74
	v_cvt_pk_bf16_f32 v184, v72, v73
	s_waitcnt lgkmcnt(0)
	v_mfma_f32_32x32x16_bf16 v[16:31], v[64:67], v[162:165], v[16:31]
	v_exp_f32_e32 v64, v78
	v_exp_f32_e32 v65, v79
	v_add_f32_e32 v66, v64, v74
	v_add_f32_e32 v226, v65, v66
	v_cvt_pk_bf16_f32 v185, v64, v65
	v_mfma_f32_32x32x16_bf16 v[0:15], v[166:169], v[162:165], v[0:15]
	s_mulk_i32 s10, 0x5800
	v_add_u32_e32 v199, s10, v242
	ds_read_b128 v[64:67], v199
	ds_read_b128 v[164:167], v199 offset:32
	ds_read_b128 v[174:177], v199 offset:64
	v_cmp_nge_f32_e64 s[6:7], s48, v226
	v_mfma_f32_32x32x16_bf16 v[16:31], v[68:71], v[170:173], v[16:31]
	v_exp_f32_e32 v68, v80
	v_exp_f32_e32 v69, v81
	v_exp_f32_e32 v80, v82
	v_add_f32_e32 v70, v69, v68
	v_cvt_pk_bf16_f32 v162, v68, v69
	v_exp_f32_e32 v81, v83
	v_add_f32_e32 v82, v80, v70
	v_mfma_f32_32x32x16_bf16 v[0:15], v[222:225], v[170:173], v[0:15]
	s_or_b64 s[8:9], s[8:9], vcc
	ds_read_b128 v[168:171], v199 offset:96
	ds_read_b128 v[208:211], v199 offset:128
	ds_read_b128 v[218:221], v199 offset:160
	s_waitcnt lgkmcnt(3)
	v_mfma_f32_32x32x16_bf16 v[64:79], v[64:67], v[98:101], 0
	v_add_f32_e32 v82, v81, v82
	v_cvt_pk_bf16_f32 v163, v80, v81
	v_mfma_f32_32x32x16_bf16 v[64:79], v[164:167], v[102:105], v[64:79]
	v_exp_f32_e32 v80, v84
	v_exp_f32_e32 v81, v85
	v_add_f32_e32 v82, v80, v82
	v_add_f32_e32 v82, v81, v82
	v_cvt_pk_bf16_f32 v164, v80, v81
	v_mfma_f32_32x32x16_bf16 v[64:79], v[174:177], v[106:109], v[64:79]
	v_exp_f32_e32 v80, v86
	v_exp_f32_e32 v81, v87
	v_add_f32_e32 v82, v80, v82
	v_add_f32_e32 v166, v81, v82
	v_cvt_pk_bf16_f32 v165, v80, v81
	s_waitcnt lgkmcnt(0)
	v_mfma_f32_32x32x16_bf16 v[64:79], v[168:171], v[110:113], v[64:79]
	ds_read_b128 v[80:83], v206 offset:35904
	ds_read_b128 v[84:87], v206 offset:35936
	ds_read_b128 v[222:225], v206 offset:40512
	ds_read_b128 v[246:249], v206 offset:40544
	v_exp_f32_e32 v88, v88
	v_exp_f32_e32 v89, v89
	v_add_f32_e32 v166, v88, v166
	v_add_f32_e32 v167, v89, v166
	v_cvt_pk_bf16_f32 v166, v88, v89
	v_mfma_f32_32x32x16_bf16 v[64:79], v[208:211], v[114:117], v[64:79]
	v_exp_f32_e32 v88, v90
	v_exp_f32_e32 v89, v91
	v_add_f32_e32 v90, v88, v167
	v_add_f32_e32 v90, v89, v90
	v_cvt_pk_bf16_f32 v167, v88, v89
	v_mfma_f32_32x32x16_bf16 v[64:79], v[218:221], v[118:121], v[64:79]
	v_exp_f32_e32 v88, v92
	v_exp_f32_e32 v89, v93
	v_add_f32_e32 v90, v88, v90
	v_add_f32_e32 v90, v89, v90
	v_cvt_pk_bf16_f32 v168, v88, v89
	s_waitcnt lgkmcnt(0)
	v_mfma_f32_32x32x16_bf16 v[48:63], v[80:83], v[178:181], v[48:63]
	v_exp_f32_e32 v80, v94
	v_exp_f32_e32 v81, v95
	v_add_f32_e32 v82, v80, v90
	v_add_f32_e32 v227, v81, v82
	v_cvt_pk_bf16_f32 v169, v80, v81
	v_mfma_f32_32x32x16_bf16 v[32:47], v[222:225], v[178:181], v[32:47]
	ds_read_b128 v[80:83], v199
	ds_read_b128 v[174:177], v199 offset:32
	ds_read_b128 v[170:173], v199 offset:64
	s_or_b64 s[6:7], s[8:9], s[6:7]
	v_cmp_nge_f32_e32 vcc, s48, v227
	s_or_b64 s[6:7], s[6:7], vcc
	s_cmp_lg_u64 s[6:7], 0
	s_cselect_b64 s[6:7], -1, 0
	s_or_b64 s[42:43], s[42:43], s[6:7]
	v_mfma_f32_32x32x16_bf16 v[48:63], v[84:87], v[182:185], v[48:63]
	v_add_f32_e64 v204, v204, v226
	v_add_f32_e64 v205, v205, v227
	s_barrier
	s_waitcnt lgkmcnt(0)
	v_mfma_f32_32x32x16_bf16 v[32:47], v[246:249], v[182:185], v[32:47]
	s_add_u32 s40, s40, 0x40000
	s_mov_b64 s[6:7], 0x2000
	s_addc_u32 s41, s41, 0
	v_lshl_add_u64 v[202:203], v[202:203], 0, s[6:7]
	s_and_b64 vcc, exec, s[44:45]
	s_cbranch_vccnz .LBB0_937
	s_mov_b32 s61, s30
	s_branch .LBB0_923
